# combination: static first phase-3 item per block + counted vmcnt waits (instead of full drains) at the late-row starts of the rows phases
# speedup vs baseline: 1.0048x; 1.0025x over previous
.LBB0_50:
	s_waitcnt vmcnt(12)
	v_mov_b32_e32 v16, v65
	v_mov_b32_e32 v184, v65
	s_nop 1
	v_permlane32_swap_b32_e32 v16, v184
	v_lshlrev_b32_e32 v24, 16, v96
	v_and_b32_e32 v25, 0xffff0000, v96
	v_ashrrev_i32_e32 v93, 31, v92
	v_lshlrev_b32_e32 v26, 16, v97
	s_waitcnt lgkmcnt(0)
	v_add_f32_e32 v16, v16, v184
	v_mov_b32_e32 v17, v16
	v_mov_b32_e32 v185, v16
	s_nop 1
	v_permlane16_swap_b32_e32 v17, v185
	v_and_b32_e32 v27, 0xffff0000, v97
	s_waitcnt lgkmcnt(0)
	v_add_f32_e32 v16, v17, v185
	s_nop 1
	v_mov_b32_dpp v17, v16 row_ror:8 row_mask:0xf bank_mask:0xf
	s_waitcnt lgkmcnt(0)
	v_add_f32_e32 v16, v16, v17
	s_nop 1
	v_mov_b32_dpp v17, v16 row_ror:4 row_mask:0xf bank_mask:0xa
	v_mov_b32_dpp v17, v16 row_ror:12 row_mask:0xf bank_mask:0x5
	s_waitcnt lgkmcnt(0)
	v_add_f32_e32 v16, v16, v17
	s_nop 1
	v_mov_b32_dpp v17, v16 quad_perm:[2,3,0,1] row_mask:0xf bank_mask:0xf
	s_waitcnt lgkmcnt(0)
	v_add_f32_e32 v16, v16, v17
	s_nop 1
	v_mov_b32_dpp v17, v16 quad_perm:[1,0,3,2] row_mask:0xf bank_mask:0xf
	s_waitcnt lgkmcnt(0)
	v_add_f32_e32 v16, v16, v17
	v_fmamk_f32 v16, v16, 0x3a800000, v198
	v_cmp_gt_f32_e64 s[4:5], s51, v16
	v_mul_f32_e32 v17, 0x4b800000, v16
	s_nop 0
	v_cndmask_b32_e64 v16, v16, v17, s[4:5]
	v_rsq_f32_e32 v16, v16
	s_nop 0
	v_mul_f32_e32 v17, 0x45800000, v16
	v_cndmask_b32_e64 v18, v16, v17, s[4:5]
	v_pk_mul_f32 v[24:25], v[18:19], v[24:25] op_sel_hi:[0,1]
	v_lshlrev_b64 v[16:17], 12, v[92:93]
	v_pk_fma_f32 v[12:13], v[152:153], v[24:25], v[12:13]
	v_pk_mul_f32 v[20:21], v[18:19], v[26:27] op_sel_hi:[0,1]
	v_pk_fma_f32 v[14:15], v[154:155], v[20:21], v[14:15]
	v_lshl_add_u64 v[20:21], v[70:71], 0, v[16:17]
	global_store_dwordx4 v[20:21], v[12:15], off nt
	v_lshlrev_b32_e32 v20, 16, v90
	v_and_b32_e32 v21, 0xffff0000, v90
	v_lshlrev_b32_e32 v22, 16, v91
	v_and_b32_e32 v23, 0xffff0000, v91
	v_pk_mul_f32 v[20:21], v[18:19], v[20:21] op_sel_hi:[0,1]
	v_pk_mul_f32 v[22:23], v[18:19], v[22:23] op_sel_hi:[0,1]
	v_lshl_add_u64 v[24:25], v[72:73], 0, v[16:17]
	v_pk_fma_f32 v[8:9], v[156:157], v[20:21], v[8:9]
	v_pk_fma_f32 v[10:11], v[22:23], v[158:159], v[10:11]
	global_store_dwordx4 v[24:25], v[8:11], off nt
	v_lshlrev_b32_e32 v12, 16, v88
	v_and_b32_e32 v13, 0xffff0000, v88
	v_lshlrev_b32_e32 v14, 16, v89
	v_and_b32_e32 v15, 0xffff0000, v89
	v_pk_mul_f32 v[12:13], v[18:19], v[12:13] op_sel_hi:[0,1]
	v_pk_fma_f32 v[4:5], v[12:13], v[160:161], v[4:5]
	v_pk_mul_f32 v[8:9], v[18:19], v[14:15] op_sel_hi:[0,1]
	v_pk_fma_f32 v[6:7], v[8:9], v[162:163], v[6:7]
	v_lshl_add_u64 v[8:9], v[74:75], 0, v[16:17]
	global_store_dwordx4 v[8:9], v[4:7], off nt
	v_lshlrev_b32_e32 v8, 16, v86
	v_and_b32_e32 v9, 0xffff0000, v86
	v_lshlrev_b32_e32 v10, 16, v87
	v_and_b32_e32 v11, 0xffff0000, v87
	v_pk_mul_f32 v[8:9], v[18:19], v[8:9] op_sel_hi:[0,1]
	v_pk_fma_f32 v[0:1], v[8:9], v[166:167], v[0:1]
	v_pk_mul_f32 v[4:5], v[18:19], v[10:11] op_sel_hi:[0,1]
	v_pk_fma_f32 v[2:3], v[4:5], v[168:169], v[2:3]
	v_lshl_add_u64 v[4:5], v[76:77], 0, v[16:17]
	global_store_dwordx4 v[4:5], v[0:3], off nt
	s_branch .LBB0_36

.LBB0_99:
	s_waitcnt vmcnt(24)
	v_mov_b32_e32 v20, v65
	v_mov_b32_e32 v184, v65
	s_nop 1
	v_permlane32_swap_b32_e32 v20, v184
	v_ashrrev_i32_e32 v89, 31, v88
	v_lshlrev_b32_e32 v22, 16, v99
	s_waitcnt lgkmcnt(0)
	v_add_f32_e32 v20, v20, v184
	v_mov_b32_e32 v21, v20
	v_mov_b32_e32 v185, v20
	s_nop 1
	v_permlane16_swap_b32_e32 v21, v185
	s_waitcnt lgkmcnt(0)
	v_add_f32_e32 v20, v21, v185
	s_nop 1
	v_mov_b32_dpp v21, v20 row_ror:8 row_mask:0xf bank_mask:0xf
	s_waitcnt lgkmcnt(0)
	v_add_f32_e32 v20, v20, v21
	s_nop 1
	v_mov_b32_dpp v21, v20 row_ror:4 row_mask:0xf bank_mask:0xa
	v_mov_b32_dpp v21, v20 row_ror:12 row_mask:0xf bank_mask:0x5
	s_waitcnt lgkmcnt(0)
	v_add_f32_e32 v20, v20, v21
	s_nop 1
	v_mov_b32_dpp v21, v20 quad_perm:[2,3,0,1] row_mask:0xf bank_mask:0xf
	s_waitcnt lgkmcnt(0)
	v_add_f32_e32 v23, v20, v21
	s_nop 1
	v_mov_b32_dpp v24, v23 quad_perm:[1,0,3,2] row_mask:0xf bank_mask:0xf
	v_lshlrev_b32_e32 v20, 16, v98
	v_and_b32_e32 v21, 0xffff0000, v98
	s_waitcnt lgkmcnt(0)
	v_add_f32_e32 v23, v23, v24
	v_fmamk_f32 v23, v23, 0x3a800000, v198
	v_mul_f32_e32 v24, 0x4b800000, v23
	v_cmp_gt_f32_e64 s[4:5], s51, v23
	s_nop 1
	v_cndmask_b32_e64 v23, v23, v24, s[4:5]
	v_rsq_f32_e32 v26, v23
	v_and_b32_e32 v23, 0xffff0000, v99
	v_lshlrev_b64 v[24:25], 12, v[88:89]
	v_lshl_add_u64 v[24:25], v[70:71], 0, v[24:25]
	v_mul_f32_e32 v27, 0x45800000, v26
	v_cndmask_b32_e64 v26, v26, v27, s[4:5]
	v_pk_mul_f32 v[20:21], v[26:27], v[20:21] op_sel_hi:[0,1]
	v_pk_mul_f32 v[22:23], v[26:27], v[22:23] op_sel_hi:[0,1]
	v_pk_fma_f32 v[12:13], v[142:143], v[20:21], v[12:13]
	v_pk_fma_f32 v[14:15], v[144:145], v[22:23], v[14:15]
	global_store_dwordx4 v[24:25], v[12:15], off
	v_lshlrev_b32_e32 v20, 16, v94
	v_and_b32_e32 v21, 0xffff0000, v94
	v_lshlrev_b32_e32 v22, 16, v95
	v_and_b32_e32 v23, 0xffff0000, v95
	v_pk_mul_f32 v[20:21], v[26:27], v[20:21] op_sel_hi:[0,1]
	v_pk_mul_f32 v[22:23], v[26:27], v[22:23] op_sel_hi:[0,1]
	v_pk_fma_f32 v[8:9], v[20:21], v[146:147], v[8:9]
	v_pk_fma_f32 v[10:11], v[22:23], v[148:149], v[10:11]
	global_store_dwordx4 v[24:25], v[8:11], off offset:1024
	v_lshlrev_b32_e32 v20, 16, v92
	v_and_b32_e32 v21, 0xffff0000, v92
	v_lshlrev_b32_e32 v22, 16, v93
	v_and_b32_e32 v23, 0xffff0000, v93
	v_pk_mul_f32 v[20:21], v[26:27], v[20:21] op_sel_hi:[0,1]
	v_pk_mul_f32 v[22:23], v[26:27], v[22:23] op_sel_hi:[0,1]
	v_pk_fma_f32 v[4:5], v[20:21], v[152:153], v[4:5]
	v_pk_fma_f32 v[6:7], v[22:23], v[154:155], v[6:7]
	global_store_dwordx4 v[24:25], v[4:7], off offset:2048
	v_lshlrev_b32_e32 v20, 16, v90
	v_and_b32_e32 v21, 0xffff0000, v90
	v_lshlrev_b32_e32 v22, 16, v91
	v_and_b32_e32 v23, 0xffff0000, v91
	v_pk_mul_f32 v[20:21], v[26:27], v[20:21] op_sel_hi:[0,1]
	v_pk_mul_f32 v[22:23], v[26:27], v[22:23] op_sel_hi:[0,1]
	v_mov_b32_e32 v26, v15
	v_mov_b32_e32 v27, v11
	v_pk_fma_f32 v[0:1], v[20:21], v[156:157], v[0:1]
	v_pk_fma_f32 v[2:3], v[22:23], v[158:159], v[2:3]
	global_store_dwordx4 v[24:25], v[0:3], off offset:3072
	v_mov_b32_e32 v22, v13
	v_mov_b32_e32 v23, v9
	v_mov_b32_e32 v20, v12
	v_mov_b32_e32 v21, v8
	v_pk_mul_f32 v[22:23], v[22:23], v[22:23]
	v_mov_b32_e32 v24, v14
	v_mov_b32_e32 v25, v10
	v_pk_fma_f32 v[20:21], v[20:21], v[20:21], v[22:23]
	v_mov_b32_e32 v22, v5
	v_pk_fma_f32 v[20:21], v[24:25], v[24:25], v[20:21]
	v_mov_b32_e32 v23, v1
	v_pk_fma_f32 v[20:21], v[26:27], v[26:27], v[20:21]
	v_pk_mul_f32 v[22:23], v[22:23], v[22:23]
	v_add_f32_e32 v28, v20, v21
	v_mov_b32_e32 v20, v4
	v_mov_b32_e32 v21, v0
	v_mov_b32_e32 v24, v6
	v_mov_b32_e32 v25, v2
	v_pk_fma_f32 v[20:21], v[20:21], v[20:21], v[22:23]
	v_mov_b32_e32 v26, v7
	v_mov_b32_e32 v27, v3
	v_pk_fma_f32 v[20:21], v[24:25], v[24:25], v[20:21]
	s_nop 0
	v_pk_fma_f32 v[20:21], v[26:27], v[26:27], v[20:21]
	s_nop 0
	v_add_f32_e32 v20, v28, v20
	v_add_f32_e32 v20, v20, v21
	v_mov_b32_e32 v21, v20
	v_mov_b32_e32 v186, v20
	s_nop 1
	v_permlane32_swap_b32_e32 v21, v186
	s_waitcnt lgkmcnt(0)
	v_add_f32_e32 v20, v21, v186
	v_mov_b32_e32 v21, v20
	v_mov_b32_e32 v187, v20
	s_nop 1
	v_permlane16_swap_b32_e32 v21, v187
	s_waitcnt lgkmcnt(0)
	v_add_f32_e32 v20, v21, v187
	s_nop 1
	v_mov_b32_dpp v21, v20 row_ror:8 row_mask:0xf bank_mask:0xf
	s_waitcnt lgkmcnt(0)
	v_add_f32_e32 v20, v20, v21
	s_nop 1
	v_mov_b32_dpp v21, v20 row_ror:4 row_mask:0xf bank_mask:0xa
	v_mov_b32_dpp v21, v20 row_ror:12 row_mask:0xf bank_mask:0x5
	s_waitcnt lgkmcnt(0)
	v_add_f32_e32 v20, v20, v21
	s_nop 1
	v_mov_b32_dpp v21, v20 quad_perm:[2,3,0,1] row_mask:0xf bank_mask:0xf
	s_waitcnt lgkmcnt(0)
	v_add_f32_e32 v20, v20, v21
	s_nop 1
	v_mov_b32_dpp v21, v20 quad_perm:[1,0,3,2] row_mask:0xf bank_mask:0xf
	s_waitcnt lgkmcnt(0)
	v_add_f32_e32 v20, v20, v21
	v_fmamk_f32 v20, v20, 0x3a800000, v198
	v_mul_f32_e32 v21, 0x4b800000, v20
	v_cmp_gt_f32_e64 s[4:5], s51, v20
	s_nop 1
	v_cndmask_b32_e64 v20, v20, v21, s[4:5]
	v_rsq_f32_e32 v22, v20
	v_lshlrev_b64 v[20:21], 11, v[88:89]
	v_lshl_add_u64 v[20:21], v[74:75], 0, v[20:21]
	v_mul_f32_e32 v23, 0x45800000, v22
	v_cndmask_b32_e64 v22, v22, v23, s[4:5]
	v_pk_mul_f32 v[12:13], v[12:13], v[22:23] op_sel_hi:[1,0]
	v_pk_mul_f32 v[14:15], v[14:15], v[22:23] op_sel_hi:[1,0]
	v_pk_mul_f32 v[8:9], v[8:9], v[22:23] op_sel_hi:[1,0]
	v_pk_mul_f32 v[10:11], v[10:11], v[22:23] op_sel_hi:[1,0]
	v_pk_mul_f32 v[12:13], v[160:161], v[12:13]
	v_pk_mul_f32 v[14:15], v[162:163], v[14:15]
	v_cvt_pk_bf16_f32 v12, v12, v13
	v_cvt_pk_bf16_f32 v13, v14, v15
	global_store_dwordx2 v[20:21], v[12:13], off
	v_pk_mul_f32 v[4:5], v[4:5], v[22:23] op_sel_hi:[1,0]
	v_pk_mul_f32 v[6:7], v[6:7], v[22:23] op_sel_hi:[1,0]
	v_pk_mul_f32 v[0:1], v[0:1], v[22:23] op_sel_hi:[1,0]
	v_pk_mul_f32 v[2:3], v[2:3], v[22:23] op_sel_hi:[1,0]
	v_pk_mul_f32 v[8:9], v[166:167], v[8:9]
	v_pk_mul_f32 v[10:11], v[10:11], v[168:169]
	v_cvt_pk_bf16_f32 v8, v8, v9
	v_cvt_pk_bf16_f32 v9, v10, v11
	global_store_dwordx2 v[20:21], v[8:9], off offset:512
	v_pk_mul_f32 v[4:5], v[4:5], v[170:171]
	v_pk_mul_f32 v[6:7], v[6:7], v[172:173]
	v_cvt_pk_bf16_f32 v4, v4, v5
	v_cvt_pk_bf16_f32 v5, v6, v7
	global_store_dwordx2 v[20:21], v[4:5], off offset:1024
	v_pk_mul_f32 v[0:1], v[0:1], v[174:175]
	v_pk_mul_f32 v[2:3], v[2:3], v[176:177]
	v_cvt_pk_bf16_f32 v0, v0, v1
	v_cvt_pk_bf16_f32 v1, v2, v3
	global_store_dwordx2 v[20:21], v[0:1], off offset:1536
	s_branch .LBB0_85

.Lp0g_0:
	v_readlane_b32 s16, v250, 53
	v_readlane_b32 s23, v250, 60
	v_mov_b32_e32 v6, s57
	v_readlane_b32 s22, v250, 59
	v_mov_b32_e32 v7, s23
	v_cndmask_b32_e32 v5, v6, v7, vcc
	v_mov_b32_e32 v8, s56
	v_mov_b32_e32 v9, s22
	v_cndmask_b32_e32 v4, v8, v9, vcc
	v_add_u32_e32 v65, s0, v63
	s_movk_i32 s6, 0x4800
	v_add_u32_e32 v64, s2, v63
	v_cmp_gt_i32_e64 s[4:5], s6, v65
	v_cmp_gt_i32_e32 vcc, s6, v64
	v_lshlrev_b64 v[0:1], 11, v[0:1]
	v_cndmask_b32_e64 v40, v63, v65, s[4:5]
	v_cndmask_b32_e32 v41, v63, v64, vcc
	v_ashrrev_i32_e32 v42, 31, v40
	v_cmp_gt_i32_e64 s[6:7], s33, v40
	v_lshl_add_u64 v[0:1], v[4:5], 0, v[0:1]
	v_lshlrev_b32_e32 v56, 3, v48
	v_cndmask_b32_e64 v5, v36, v37, s[6:7]
	v_cndmask_b32_e64 v4, v38, v39, s[6:7]
	v_mov_b32_e32 v57, v197
	v_lshl_add_u64 v[72:73], v[0:1], 0, v[56:57]
	v_readlane_b32 s17, v250, 54
	v_readlane_b32 s18, v250, 55
	v_readlane_b32 s19, v250, 56
	v_readlane_b32 s20, v250, 57
	v_readlane_b32 s21, v250, 58
	v_readlane_b32 s24, v250, 61
	v_readlane_b32 s25, v250, 62
	v_readlane_b32 s26, v250, 63
	v_readlane_b32 s27, v249, 0
	v_readlane_b32 s28, v249, 1
	v_readlane_b32 s29, v249, 2
	v_readlane_b32 s30, v249, 3
	v_readlane_b32 s31, v249, 4
	v_mov_b32_e32 v6, v29
	v_mov_b32_e32 v7, v25
	v_mov_b32_e32 v2, v28
	v_mov_b32_e32 v3, v24
	v_mov_b32_e32 v14, v21
	v_mov_b32_e32 v15, v17
	v_pk_mul_f32 v[6:7], v[6:7], v[6:7]
	v_mov_b32_e32 v8, v30
	v_mov_b32_e32 v9, v26
	v_mov_b32_e32 v12, v20
	v_mov_b32_e32 v13, v16
	v_pk_mul_f32 v[14:15], v[14:15], v[14:15]
	v_pk_fma_f32 v[2:3], v[2:3], v[2:3], v[6:7]
	v_mov_b32_e32 v10, v31
	v_mov_b32_e32 v11, v27
	v_mov_b32_e32 v32, v22
	v_mov_b32_e32 v33, v18
	v_pk_fma_f32 v[6:7], v[12:13], v[12:13], v[14:15]
	v_pk_fma_f32 v[2:3], v[8:9], v[8:9], v[2:3]
	v_mov_b32_e32 v34, v23
	v_mov_b32_e32 v35, v19
	v_pk_fma_f32 v[6:7], v[32:33], v[32:33], v[6:7]
	v_pk_fma_f32 v[2:3], v[10:11], v[10:11], v[2:3]
	v_pk_fma_f32 v[6:7], v[34:35], v[34:35], v[6:7]
	v_add_f32_e32 v2, v2, v3
	v_add_f32_e32 v2, v2, v6
	v_add_f32_e32 v2, v2, v7
	v_mov_b32_e32 v3, v2
	v_mov_b32_e32 v184, v2
	s_nop 1
	v_permlane32_swap_b32_e32 v3, v184
	v_add_u32_e32 v6, 0xffffc000, v40
	v_ashrrev_i32_e32 v7, 31, v41
	v_add_u32_e32 v8, 0xffffc000, v41
	s_waitcnt lgkmcnt(0)
	v_add_f32_e32 v9, v3, v184
	v_mov_b32_e32 v10, v9
	v_mov_b32_e32 v185, v9
	s_nop 1
	v_permlane16_swap_b32_e32 v10, v185
	v_cndmask_b32_e64 v3, 0, v42, s[6:7]
	v_cndmask_b32_e64 v2, v6, v40, s[6:7]
	v_cmp_gt_i32_e64 s[6:7], s33, v41
	v_lshlrev_b64 v[0:1], 12, v[2:3]
	s_waitcnt lgkmcnt(0)
	v_add_f32_e32 v10, v10, v185
	s_nop 1
	v_mov_b32_dpp v11, v10 row_ror:8 row_mask:0xf bank_mask:0xf
	v_cndmask_b32_e64 v7, 0, v7, s[6:7]
	v_cndmask_b32_e64 v6, v8, v41, s[6:7]
	v_lshlrev_b64 v[2:3], 12, v[6:7]
	v_lshl_add_u64 v[0:1], v[4:5], 0, v[0:1]
	s_waitcnt lgkmcnt(0)
	v_add_f32_e32 v10, v10, v11
	s_nop 1
	v_mov_b32_dpp v11, v10 row_ror:4 row_mask:0xf bank_mask:0xa
	v_mov_b32_dpp v11, v10 row_ror:12 row_mask:0xf bank_mask:0x5
	v_lshl_add_u64 v[0:1], v[0:1], 0, v[54:55]
	v_cndmask_b32_e64 v9, v36, v37, s[6:7]
	v_cndmask_b32_e64 v8, v38, v39, s[6:7]
	global_load_dwordx4 v[44:47], v[0:1], off nt
	global_load_dwordx4 v[40:43], v[0:1], off offset:1024 nt
	global_load_dwordx4 v[36:39], v[0:1], off offset:2048 nt
	global_load_dwordx4 v[32:35], v[0:1], off offset:3072 nt
	s_waitcnt lgkmcnt(0)
	v_add_f32_e32 v6, v10, v11
	s_nop 1
	v_mov_b32_dpp v7, v6 quad_perm:[2,3,0,1] row_mask:0xf bank_mask:0xf
	v_lshl_add_u64 v[2:3], v[8:9], 0, v[2:3]
	v_lshl_add_u64 v[2:3], v[2:3], 0, v[54:55]
	s_waitcnt lgkmcnt(0)
	v_add_f32_e32 v4, v6, v7
	s_nop 1
	v_mov_b32_dpp v5, v4 quad_perm:[1,0,3,2] row_mask:0xf bank_mask:0xf
	s_waitcnt lgkmcnt(0)
	v_add_f32_e32 v0, v4, v5
	v_fmamk_f32 v0, v0, 0x3a800000, v198
	v_mul_f32_e32 v1, 0x4b800000, v0
	v_cmp_gt_f32_e64 s[6:7], s51, v0
	s_nop 1
	v_cndmask_b32_e64 v0, v0, v1, s[6:7]
	v_rsq_f32_e32 v55, v0
	global_load_dwordx4 v[12:15], v[2:3], off nt
	global_load_dwordx4 v[8:11], v[2:3], off offset:1024 nt
	global_load_dwordx4 v[4:7], v[2:3], off offset:2048 nt
	s_nop 0
	global_load_dwordx4 v[0:3], v[2:3], off offset:3072 nt
	v_mul_f32_e32 v74, 0x45800000, v55
	v_cndmask_b32_e64 v74, v55, v74, s[6:7]
	v_pk_mul_f32 v[28:29], v[28:29], v[74:75] op_sel_hi:[1,0]
	v_pk_mul_f32 v[30:31], v[30:31], v[74:75] op_sel_hi:[1,0]
	s_waitcnt vmcnt(8)
	v_pk_mul_f32 v[28:29], v[76:77], v[28:29]
	v_pk_mul_f32 v[30:31], v[78:79], v[30:31]
	v_cvt_pk_bf16_f32 v28, v28, v29
	v_cvt_pk_bf16_f32 v29, v30, v31
	global_store_dwordx2 v[72:73], v[28:29], off
	v_pk_mul_f32 v[24:25], v[24:25], v[74:75] op_sel_hi:[1,0]
	v_pk_mul_f32 v[26:27], v[26:27], v[74:75] op_sel_hi:[1,0]
	v_pk_mul_f32 v[20:21], v[20:21], v[74:75] op_sel_hi:[1,0]
	v_pk_mul_f32 v[22:23], v[22:23], v[74:75] op_sel_hi:[1,0]
	v_pk_mul_f32 v[16:17], v[16:17], v[74:75] op_sel_hi:[1,0]
	v_pk_mul_f32 v[18:19], v[18:19], v[74:75] op_sel_hi:[1,0]
	v_pk_mul_f32 v[24:25], v[82:83], v[24:25]
	v_pk_mul_f32 v[26:27], v[84:85], v[26:27]
	v_cvt_pk_bf16_f32 v24, v24, v25
	v_cvt_pk_bf16_f32 v25, v26, v27
	global_store_dwordx2 v[72:73], v[24:25], off offset:512
	v_pk_mul_f32 v[20:21], v[20:21], v[86:87]
	v_pk_mul_f32 v[22:23], v[22:23], v[88:89]
	v_cvt_pk_bf16_f32 v20, v20, v21
	v_cvt_pk_bf16_f32 v21, v22, v23
	global_store_dwordx2 v[72:73], v[20:21], off offset:1024
	v_pk_mul_f32 v[16:17], v[16:17], v[90:91]
	v_pk_mul_f32 v[18:19], v[18:19], v[92:93]
	v_cvt_pk_bf16_f32 v16, v16, v17
	v_cvt_pk_bf16_f32 v17, v18, v19
	global_store_dwordx2 v[72:73], v[16:17], off offset:1536
	s_and_saveexec_b64 s[6:7], s[4:5]
	s_cbranch_execz .LBB0_529
	s_waitcnt vmcnt(4)
	v_readlane_b32 s16, v249, 21
	v_readlane_b32 s18, v249, 25
	v_readlane_b32 s17, v249, 22
	v_readlane_b32 s19, v249, 26
	v_cmp_gt_i32_e64 s[4:5], s33, v65
	v_mov_b32_e32 v16, s17
	v_mov_b32_e32 v17, s19
	v_cndmask_b32_e64 v17, v16, v17, s[4:5]
	v_mov_b32_e32 v16, s16
	v_mov_b32_e32 v18, s18
	v_cndmask_b32_e64 v16, v16, v18, s[4:5]
	v_lshl_add_u64 v[20:21], v[16:17], 0, v[196:197]
	s_and_b64 s[40:41], exec, s[4:5]
	s_cbranch_scc1 .Lp0g_1
	global_load_dwordx4 v[76:79], v[20:21], off
	global_load_dwordx4 v[82:85], v[20:21], off offset:1024
	global_load_dwordx4 v[86:89], v[20:21], off offset:2048
	global_load_dwordx4 v[90:93], v[20:21], off offset:3072
	s_waitcnt vmcnt(0)

.LBB0_529:
	s_or_b64 exec, exec, s[6:7]
	s_and_saveexec_b64 s[4:5], vcc
	s_cbranch_execz .LBB0_526
	s_nop 0
	v_readlane_b32 s6, v249, 21
	v_readlane_b32 s16, v249, 25
	v_readlane_b32 s7, v249, 22
	v_readlane_b32 s17, v249, 26
	v_cmp_gt_i32_e32 vcc, s33, v64
	v_mov_b32_e32 v16, s7
	v_mov_b32_e32 v17, s17
	v_cndmask_b32_e32 v17, v16, v17, vcc
	v_mov_b32_e32 v16, s6
	v_mov_b32_e32 v18, s16
	v_cndmask_b32_e32 v16, v16, v18, vcc
	v_lshl_add_u64 v[20:21], v[16:17], 0, v[196:197]
	s_cbranch_vccnz .Lp0g_2
	global_load_dwordx4 v[76:79], v[20:21], off
	global_load_dwordx4 v[82:85], v[20:21], off offset:1024
	global_load_dwordx4 v[86:89], v[20:21], off offset:2048
	global_load_dwordx4 v[90:93], v[20:21], off offset:3072
	s_waitcnt vmcnt(0)
